# mixer prompt band attention: cross-half row max via v_permlane32_swap instead of ds_bpermute + lgkmcnt wait
# baseline (speedup 1.0000x reference)
; __device__ __forceinline__ void attn_score(AttnState& st, bf16x8 (&pf)[2], const bf16x8 (&kf)[4], const bf16x8 (&qf)[4], int j, int qi, bool mask_hi,
;                                            LAS float* tab, float tconst, int lane) {
;     ...
;     float mx = s[0];
; #pragma unroll
;     for (int e = 1; e < 16; ++e) mx = fmaxf(mx, s[e]);
;     mx = fmaxf(mx, __shfl_xor(mx, 32));
;     if (__any(mx > st.mrun + 8.0f)) {
;         const float mnew = fmaxf(st.mrun, mx);
;         const float alpha = __builtin_amdgcn_exp2f(st.mrun - mnew);
;         st.mrun = mnew; st.lsum *= alpha;
; #pragma unroll
;         for (int db = 0; db < 2; ++db)
; #pragma unroll
;             for (int e = 0; e < 16; ++e) st.O[db][e] *= alpha;
;     }
.LBB0_701:
	s_nop 5
	v_max_f32_e32 v82, v67, v67
	v_max_f32_e32 v83, v66, v66
	v_max_f32_e32 v82, v83, v82
	v_max3_f32 v82, v82, v68, v69
	v_max3_f32 v82, v82, v70, v71
	v_max3_f32 v82, v82, v72, v73
	v_max3_f32 v82, v82, v74, v75
	v_max3_f32 v82, v82, v76, v77
	v_max3_f32 v82, v82, v78, v79
	v_max3_f32 v82, v82, v80, v81
	v_mov_b32_e32 v83, v82
	s_waitcnt lgkmcnt(0)
	s_nop 1
	v_permlane32_swap_b32_e32 v83, v82
	s_nop 1
	v_max_f32_e32 v82, v82, v83
	v_add_f32_e32 v83, 0x41000000, v249
	v_cmp_gt_f32_e32 vcc, v82, v83
	s_cbranch_vccz .LBB0_703
	v_max_f32_e32 v82, v82, v82
	v_max_f32_e32 v83, v249, v249
	v_max_f32_e32 v83, v83, v82
	v_sub_f32_e32 v82, v249, v83
	v_exp_f32_e32 v82, v82
	v_mov_b32_e32 v249, v83
	v_mul_f32_e32 v229, v229, v82
	v_pk_mul_f32 v[64:65], v[64:65], v[82:83] op_sel_hi:[1,0]
	v_pk_mul_f32 v[62:63], v[62:63], v[82:83] op_sel_hi:[1,0]
	v_pk_mul_f32 v[60:61], v[60:61], v[82:83] op_sel_hi:[1,0]
	v_pk_mul_f32 v[58:59], v[58:59], v[82:83] op_sel_hi:[1,0]
	v_pk_mul_f32 v[56:57], v[56:57], v[82:83] op_sel_hi:[1,0]
	v_pk_mul_f32 v[54:55], v[54:55], v[82:83] op_sel_hi:[1,0]
	v_pk_mul_f32 v[52:53], v[52:53], v[82:83] op_sel_hi:[1,0]
	v_pk_mul_f32 v[50:51], v[50:51], v[82:83] op_sel_hi:[1,0]
	v_pk_mul_f32 v[48:49], v[48:49], v[82:83] op_sel_hi:[1,0]
	v_pk_mul_f32 v[46:47], v[46:47], v[82:83] op_sel_hi:[1,0]
	v_pk_mul_f32 v[44:45], v[44:45], v[82:83] op_sel_hi:[1,0]
	v_pk_mul_f32 v[42:43], v[42:43], v[82:83] op_sel_hi:[1,0]
	v_pk_mul_f32 v[40:41], v[40:41], v[82:83] op_sel_hi:[1,0]
	v_pk_mul_f32 v[38:39], v[38:39], v[82:83] op_sel_hi:[1,0]
	v_pk_mul_f32 v[36:37], v[36:37], v[82:83] op_sel_hi:[1,0]
	v_pk_mul_f32 v[34:35], v[34:35], v[82:83] op_sel_hi:[1,0]

; __device__ __forceinline__ void attn_score(AttnState& st, bf16x8 (&pf)[2], const bf16x8 (&kf)[4], const bf16x8 (&qf)[4], int j, int qi, bool mask_hi,
;                                            LAS float* tab, float tconst, int lane) {
;     ...
;     float mx = s[0];
; #pragma unroll
;     for (int e = 1; e < 16; ++e) mx = fmaxf(mx, s[e]);
;     mx = fmaxf(mx, __shfl_xor(mx, 32));
;     if (__any(mx > st.mrun + 8.0f)) {
;         const float mnew = fmaxf(st.mrun, mx);
;         const float alpha = __builtin_amdgcn_exp2f(st.mrun - mnew);
;         st.mrun = mnew; st.lsum *= alpha;
; #pragma unroll
;         for (int db = 0; db < 2; ++db)
; #pragma unroll
;             for (int e = 0; e < 16; ++e) st.O[db][e] *= alpha;
;     }
.LBB0_707:
	s_nop 5
	v_max_f32_e32 v82, v67, v67
	v_max_f32_e32 v83, v66, v66
	v_max_f32_e32 v82, v83, v82
	v_max3_f32 v82, v82, v68, v69
	v_max3_f32 v82, v82, v70, v71
	v_max3_f32 v82, v82, v72, v73
	v_max3_f32 v82, v82, v74, v75
	v_max3_f32 v82, v82, v76, v77
	v_max3_f32 v82, v82, v78, v79
	v_max3_f32 v82, v82, v80, v81
	v_mov_b32_e32 v83, v82
	s_waitcnt lgkmcnt(0)
	s_nop 1
	v_permlane32_swap_b32_e32 v83, v82
	s_nop 1
	v_max_f32_e32 v82, v82, v83
	v_add_f32_e32 v83, 0x41000000, v0
	v_cmp_gt_f32_e32 vcc, v82, v83
	s_cbranch_vccz .LBB0_709
	v_max_f32_e32 v82, v82, v82
	v_max_f32_e32 v83, v0, v0
	v_max_f32_e32 v82, v83, v82
	v_sub_f32_e32 v0, v0, v82
	v_exp_f32_e32 v0, v0
	s_nop 0
	v_mul_f32_e32 v207, v207, v0
	v_pk_mul_f32 v[32:33], v[32:33], v[0:1] op_sel_hi:[1,0]
	v_pk_mul_f32 v[30:31], v[30:31], v[0:1] op_sel_hi:[1,0]
	v_pk_mul_f32 v[28:29], v[28:29], v[0:1] op_sel_hi:[1,0]
	v_pk_mul_f32 v[26:27], v[26:27], v[0:1] op_sel_hi:[1,0]
	v_pk_mul_f32 v[24:25], v[24:25], v[0:1] op_sel_hi:[1,0]
	v_pk_mul_f32 v[22:23], v[22:23], v[0:1] op_sel_hi:[1,0]
	v_pk_mul_f32 v[20:21], v[20:21], v[0:1] op_sel_hi:[1,0]
	v_pk_mul_f32 v[18:19], v[18:19], v[0:1] op_sel_hi:[1,0]
	v_pk_mul_f32 v[16:17], v[16:17], v[0:1] op_sel_hi:[1,0]
	v_pk_mul_f32 v[14:15], v[14:15], v[0:1] op_sel_hi:[1,0]
	v_pk_mul_f32 v[12:13], v[12:13], v[0:1] op_sel_hi:[1,0]
	v_pk_mul_f32 v[10:11], v[10:11], v[0:1] op_sel_hi:[1,0]
	v_pk_mul_f32 v[8:9], v[8:9], v[0:1] op_sel_hi:[1,0]
	v_pk_mul_f32 v[6:7], v[6:7], v[0:1] op_sel_hi:[1,0]
	v_pk_mul_f32 v[4:5], v[4:5], v[0:1] op_sel_hi:[1,0]
	v_pk_mul_f32 v[2:3], v[2:3], v[0:1] op_sel_hi:[1,0]
	v_mov_b32_e32 v0, v82
